# prompt-attention loop: packed fp32 VALU (v_pk_mul/add/fma_f32) split into scalar pairs
# speedup vs baseline: 1.0107x; 1.0032x over previous
; #define LAS __attribute__((address_space(3)))
; __device__ __forceinline__ unsigned pk2(float lo, float hi) { const f32x2_ v = {lo, hi}; return __builtin_bit_cast(unsigned, __builtin_convertvector(v, bf16x2_)); }
; __device__ __forceinline__ void attn_prompt_unit(const PP P, LAS unsigned char* lds, int b, int h, int qt) {
;     ...
;     for (int kt = 0; kt < nt_blk; ++kt) {
;         const bool more = kt + 1 < nt_blk;
;         if (more) { rk = *(const u32x4*)(gk + (size_t)(kt + 1) * 64 * 512); rv = *(const u32x4*)(gv + (kt + 1) * 64); if (tid < 256) rp = *(const u32x4*)(gp + (size_t)(kt + 1) * 64 * 32); }
;         if (kt < nt_w) {
;             const LAS unsigned char* kb = lds + (kt & 1) * AT_STAGE; const LAS unsigned char* vb = kb + AT_V;
;             f32x4 s[2][4];
; #pragma unroll
;             for (int sb = 0; sb < 4; ++sb) { s[0][sb] = (f32x4){0.f, 0.f, 0.f, 0.f}; s[1][sb] = (f32x4){0.f, 0.f, 0.f, 0.f};
; #pragma unroll
;                 for (int ks = 0; ks < 3; ++ks) { const bf16x8 kf = *(const LAS bf16x8*)(kb + (16 * sb + fr) * AT_KROW + ks * 64 + fq * 16);
;                     s[0][sb] = mfma16(kf, Qb[0][ks], s[0][sb]); s[1][sb] = mfma16(kf, Qb[1][ks], s[1][sb]); } }
;             bf16x8 Pb[2][2];
; #pragma unroll
;             for (int g = 0; g < 2; ++g) {
;                 float mx = -INFINITY;
; #pragma unroll
;                 for (int sb = 0; sb < 4; ++sb) mx = fmaxf(mx, fmaxf(fmaxf(s[g][sb][0], s[g][sb][1]), fmaxf(s[g][sb][2], s[g][sb][3])));
;                 mx = fmaxf(mx, xor16_get(mx)); mx = xor32_max(mx);
;                 const float mnew = fmaxf(m[g], mx), alpha = __builtin_amdgcn_exp2f(m[g] - mnew); m[g] = mnew;
;                 float ps = 0.f; float p[4][4];
; #pragma unroll
;                 for (int sb = 0; sb < 4; ++sb)
; #pragma unroll
;                     for (int j = 0; j < 4; ++j) { p[sb][j] = __builtin_amdgcn_exp2f(s[g][sb][j] - mnew); ps += p[sb][j]; }
;                 lsum[g] = lsum[g] * alpha + ps;
; #pragma unroll
;                 for (int kk = 0; kk < 2; ++kk) { u32x4 pw; pw.x = pk2(p[2 * kk][0], p[2 * kk][1]); pw.y = pk2(p[2 * kk][2], p[2 * kk][3]); pw.z = pk2(p[2 * kk + 1][0], p[2 * kk + 1][1]); pw.w = pk2(p[2 * kk + 1][2], p[2 * kk + 1][3]);
;                     Pb[g][kk] = __builtin_bit_cast(bf16x8, pw); }
; #pragma unroll
;                 for (int nt = 0; nt < 4; ++nt) O[g][nt] = O[g][nt] * alpha;
.LBB0_44:
	s_or_b64 exec, exec, s[2:3]
	v_cmp_le_i32_e32 vcc, s26, v121
	s_and_saveexec_b64 s[2:3], vcc
	s_cbranch_execz .LBB0_46
	s_bitcmp1_b32 s26, 0
	s_cselect_b32 s27, 0x5800, 0
	s_add_i32 s27, s27, 0
	v_add3_u32 v73, s27, v98, v147
	ds_read_b128 v[200:203], v73
	ds_read_b128 v[204:207], v73 offset:64
	ds_read_b128 v[208:211], v73 offset:128
	ds_read_b128 v[212:215], v73 offset:3328
	ds_read_b128 v[216:219], v73 offset:3392
	ds_read_b128 v[220:223], v73 offset:3456
	ds_read_b128 v[224:227], v73 offset:6656
	ds_read_b128 v[228:231], v73 offset:6720
	ds_read_b128 v[232:235], v73 offset:6784
	ds_read_b128 v[236:239], v73 offset:9984
	ds_read_b128 v[240:243], v73 offset:10048
	ds_read_b128 v[244:247], v73 offset:10112
	s_waitcnt lgkmcnt(11)
	v_mfma_f32_16x16x32_bf16 v[154:157], v[200:203], v[40:43], 0
	v_mfma_f32_16x16x32_bf16 v[80:83], v[200:203], v[28:31], 0
	s_waitcnt lgkmcnt(10)
	v_mfma_f32_16x16x32_bf16 v[154:157], v[204:207], v[36:39], v[154:157]
	v_mfma_f32_16x16x32_bf16 v[80:83], v[204:207], v[20:23], v[80:83]
	s_waitcnt lgkmcnt(9)
	v_mfma_f32_16x16x32_bf16 v[154:157], v[208:211], v[32:35], v[154:157]
	v_mfma_f32_16x16x32_bf16 v[80:83], v[208:211], v[16:19], v[80:83]
	s_waitcnt lgkmcnt(8)
	v_mfma_f32_16x16x32_bf16 v[158:161], v[212:215], v[40:43], 0
	v_mfma_f32_16x16x32_bf16 v[84:87], v[212:215], v[28:31], 0
	s_waitcnt lgkmcnt(7)
	v_mfma_f32_16x16x32_bf16 v[158:161], v[216:219], v[36:39], v[158:161]
	v_mfma_f32_16x16x32_bf16 v[84:87], v[216:219], v[20:23], v[84:87]
	s_waitcnt lgkmcnt(6)
	v_mfma_f32_16x16x32_bf16 v[158:161], v[220:223], v[32:35], v[158:161]
	v_mfma_f32_16x16x32_bf16 v[84:87], v[220:223], v[16:19], v[84:87]
	s_waitcnt lgkmcnt(5)
	v_mfma_f32_16x16x32_bf16 v[178:181], v[224:227], v[40:43], 0
	v_mfma_f32_16x16x32_bf16 v[88:91], v[224:227], v[28:31], 0
	s_waitcnt lgkmcnt(4)
	v_mfma_f32_16x16x32_bf16 v[178:181], v[228:231], v[36:39], v[178:181]
	v_mfma_f32_16x16x32_bf16 v[88:91], v[228:231], v[20:23], v[88:91]
	s_waitcnt lgkmcnt(3)
	v_mfma_f32_16x16x32_bf16 v[178:181], v[232:235], v[32:35], v[178:181]
	v_mfma_f32_16x16x32_bf16 v[88:91], v[232:235], v[16:19], v[88:91]
	s_waitcnt lgkmcnt(2)
	v_mfma_f32_16x16x32_bf16 v[182:185], v[236:239], v[40:43], 0
	v_mfma_f32_16x16x32_bf16 v[92:95], v[236:239], v[28:31], 0
	s_waitcnt lgkmcnt(1)
	v_mfma_f32_16x16x32_bf16 v[182:185], v[240:243], v[36:39], v[182:185]
	v_mfma_f32_16x16x32_bf16 v[92:95], v[240:243], v[20:23], v[92:95]
	s_waitcnt lgkmcnt(0)
	v_mfma_f32_16x16x32_bf16 v[182:185], v[244:247], v[32:35], v[182:185]
	v_mfma_f32_16x16x32_bf16 v[92:95], v[244:247], v[16:19], v[92:95]
	s_nop 7
	s_nop 1
	v_max_f32_e32 v125, v83, v83
	v_max_f32_e32 v73, v157, v157
	v_max_f32_e32 v139, v86, v86
	s_nop 1
	v_max_f32_e32 v74, v156, v156
	v_max_f32_e32 v73, v74, v73
	v_max_f32_e32 v74, v161, v161
	v_max_f32_e32 v75, v160, v160
	v_max_f32_e32 v74, v75, v74
	v_max3_f32 v73, v154, v155, v73
	v_max3_f32 v74, v158, v159, v74
	v_max3_f32 v73, v73, s37, v74
	v_max_f32_e32 v74, v181, v181
	v_max_f32_e32 v75, v180, v180
	v_max_f32_e32 v74, v75, v74
	v_max_f32_e32 v75, v185, v185
	v_max_f32_e32 v76, v184, v184
	v_max_f32_e32 v75, v76, v75
	v_max3_f32 v74, v178, v179, v74
	v_max3_f32 v75, v182, v183, v75
	v_max3_f32 v73, v73, v74, v75
	ds_swizzle_b32 v74, v73 offset:swizzle(SWAP,16)
	v_max_f32_e32 v141, v94, v94
	s_waitcnt lgkmcnt(0)
	v_max_f32_e32 v74, v74, v74
	v_max_f32_e32 v73, v73, v74
	v_mov_b32_e32 v74, v73
	s_nop 1
	v_permlane32_swap_b32_e32 v73, v74
	v_max3_f32 v123, v72, v73, v74
	v_sub_f32_e32 v72, v72, v123
	v_exp_f32_e32 v136, v72
	v_sub_f32_e32 v72, v154, v123
	v_exp_f32_e32 v138, v72
	v_sub_f32_e32 v72, v155, v123
	v_mul_f32_e32 v46, v136, v46
	v_mul_f32_e32 v47, v136, v47
	v_mul_f32_e32 v44, v136, v44
	v_mul_f32_e32 v45, v136, v45
	v_mul_f32_e32 v54, v136, v54
	v_mul_f32_e32 v55, v136, v55
	v_mul_f32_e32 v52, v136, v52
	v_mul_f32_e32 v53, v136, v53
	v_mul_f32_e32 v58, v136, v58
	v_mul_f32_e32 v59, v136, v59
	v_mul_f32_e32 v56, v136, v56
	v_mul_f32_e32 v57, v136, v57
	v_mul_f32_e32 v70, v136, v70
	v_mul_f32_e32 v71, v136, v71
	v_mul_f32_e32 v68, v136, v68
	v_mul_f32_e32 v69, v136, v69
	v_max_f32_e32 v137, v82, v82
	v_max_f32_e32 v125, v137, v125
	v_max_f32_e32 v137, v87, v87
	v_max_f32_e32 v137, v139, v137
	v_max3_f32 v125, v80, v81, v125
	v_max3_f32 v137, v84, v85, v137
	v_max3_f32 v125, v125, s37, v137
	v_max_f32_e32 v137, v91, v91
	v_max_f32_e32 v139, v90, v90
	v_max_f32_e32 v137, v139, v137
	v_max_f32_e32 v139, v95, v95
	v_max_f32_e32 v139, v141, v139
	v_max3_f32 v137, v88, v89, v137
	v_max3_f32 v139, v92, v93, v139
	v_max3_f32 v125, v125, v137, v139
	ds_swizzle_b32 v137, v125 offset:swizzle(SWAP,16)
	v_exp_f32_e32 v140, v72
	v_sub_f32_e32 v72, v156, v123
	v_exp_f32_e32 v154, v72
	v_sub_f32_e32 v72, v157, v123
	s_waitcnt lgkmcnt(0)
; #define LAS __attribute__((address_space(3)))
; __device__ __forceinline__ unsigned pk2(float lo, float hi) { const f32x2_ v = {lo, hi}; return __builtin_bit_cast(unsigned, __builtin_convertvector(v, bf16x2_)); }
; __device__ __forceinline__ f32x4 mfma16(bf16x8 a, bf16x8 b, f32x4 c) { return __builtin_amdgcn_mfma_f32_16x16x32_bf16(a, b, c, 0, 0, 0); }
; __device__ __forceinline__ void attn_prompt_unit(const PP P, LAS unsigned char* lds, int b, int h, int qt) {
;     ...
;                 const float mnew = fmaxf(m[g], mx), alpha = __builtin_amdgcn_exp2f(m[g] - mnew); m[g] = mnew;
;                 float ps = 0.f; float p[4][4];
; #pragma unroll
;                 for (int sb = 0; sb < 4; ++sb)
; #pragma unroll
;                     for (int j = 0; j < 4; ++j) { p[sb][j] = __builtin_amdgcn_exp2f(s[g][sb][j] - mnew); ps += p[sb][j]; }
;                 lsum[g] = lsum[g] * alpha + ps;
; #pragma unroll
;                 for (int kk = 0; kk < 2; ++kk) { u32x4 pw; pw.x = pk2(p[2 * kk][0], p[2 * kk][1]); pw.y = pk2(p[2 * kk][2], p[2 * kk][3]); pw.z = pk2(p[2 * kk + 1][0], p[2 * kk + 1][1]); pw.w = pk2(p[2 * kk + 1][2], p[2 * kk + 1][3]);
;                     Pb[g][kk] = __builtin_bit_cast(bf16x8, pw); }
; #pragma unroll
;                 for (int nt = 0; nt < 4; ++nt) O[g][nt] = O[g][nt] * alpha;
;             }
; #pragma unroll
;             for (int nt = 0; nt < 4; ++nt)
; #pragma unroll
;                 for (int kk = 0; kk < 2; ++kk) { const LAS unsigned char* vp = vb + (16 * nt + fr) * AT_VROW + kk * 64 + fq * 8;
;                     const s16x4 a = *(const LAS s16x4*)vp, c = *(const LAS s16x4*)(vp + 32);
;                     bf16x8 vf; vf[0] = a[0]; vf[1] = a[1]; vf[2] = a[2]; vf[3] = a[3]; vf[4] = c[0]; vf[5] = c[1]; vf[6] = c[2]; vf[7] = c[3];
;                     O[0][nt] = mfma16(vf, Pb[0][kk], O[0][nt]); O[1][nt] = mfma16(vf, Pb[1][kk], O[1][nt]); }
	v_max_f32_e32 v137, v137, v137
	v_max_f32_e32 v125, v125, v137
	v_mov_b32_e32 v137, v125
	s_nop 1
	v_permlane32_swap_b32_e32 v125, v137
	v_max3_f32 v125, v24, v125, v137
	v_sub_f32_e32 v24, v24, v125
	v_exp_f32_e32 v137, v24
	v_sub_f32_e32 v24, v80, v125
	v_exp_f32_e32 v139, v24
	v_sub_f32_e32 v24, v81, v125
	v_exp_f32_e32 v141, v24
	v_sub_f32_e32 v24, v82, v125
	v_exp_f32_e32 v155, v24
	v_sub_f32_e32 v24, v83, v125
	v_exp_f32_e32 v156, v72
	v_sub_f32_e32 v72, v158, v123
	v_exp_f32_e32 v157, v24
	v_sub_f32_e32 v24, v84, v125
	v_exp_f32_e32 v158, v72
	v_sub_f32_e32 v72, v159, v123
	v_exp_f32_e32 v159, v24
	v_sub_f32_e32 v24, v85, v125
	v_exp_f32_e32 v162, v72
	v_sub_f32_e32 v72, v160, v123
	v_exp_f32_e32 v163, v24
	v_sub_f32_e32 v24, v86, v125
	v_exp_f32_e32 v160, v72
	v_sub_f32_e32 v72, v161, v123
	v_exp_f32_e32 v161, v24
	v_sub_f32_e32 v24, v87, v125
	v_exp_f32_e32 v186, v72
	v_sub_f32_e32 v72, v178, v123
	v_exp_f32_e32 v187, v24
	v_sub_f32_e32 v24, v88, v125
	v_exp_f32_e32 v178, v72
	v_sub_f32_e32 v72, v179, v123
	v_exp_f32_e32 v179, v24
	v_sub_f32_e32 v24, v89, v125
	v_exp_f32_e32 v188, v72
	v_sub_f32_e32 v72, v180, v123
	v_exp_f32_e32 v189, v24
	v_sub_f32_e32 v24, v90, v125
	v_exp_f32_e32 v180, v72
	v_sub_f32_e32 v72, v181, v123
	v_exp_f32_e32 v181, v24
	v_sub_f32_e32 v24, v91, v125
	v_exp_f32_e32 v190, v72
	v_sub_f32_e32 v72, v182, v123
	v_exp_f32_e32 v191, v24
	v_sub_f32_e32 v24, v92, v125
	v_exp_f32_e32 v182, v72
	v_sub_f32_e32 v72, v183, v123
	v_exp_f32_e32 v183, v24
	v_sub_f32_e32 v24, v93, v125
	v_exp_f32_e32 v192, v72
	v_sub_f32_e32 v72, v184, v123
	v_exp_f32_e32 v193, v24
	v_sub_f32_e32 v24, v94, v125
	v_exp_f32_e32 v184, v72
	v_sub_f32_e32 v72, v185, v123
	v_exp_f32_e32 v185, v24
	v_sub_f32_e32 v24, v95, v125
	v_exp_f32_e32 v195, v24
	v_mov_b32_e32 v24, v137
	v_mul_f32_e32 v6, v24, v6
	v_mul_f32_e32 v7, v24, v7
	v_mul_f32_e32 v4, v24, v4
	v_mul_f32_e32 v5, v24, v5
	v_mul_f32_e32 v2, v24, v2
	v_mul_f32_e32 v3, v24, v3
	v_mul_f32_e32 v0, v24, v0
	v_mul_f32_e32 v1, v24, v1
	v_mul_f32_e32 v10, v24, v10
	v_mul_f32_e32 v11, v24, v11
	v_mul_f32_e32 v8, v24, v8
	v_mul_f32_e32 v9, v24, v9
	v_mul_f32_e32 v14, v24, v14
	v_mul_f32_e32 v15, v24, v15
	v_mul_f32_e32 v12, v24, v12
	v_mul_f32_e32 v13, v24, v13
	v_add3_u32 v24, s27, v96, v148
	v_add_u32_e32 v92, 0x3000, v24
	ds_read2_b64 v[88:91], v92 offset0:128 offset1:132
	v_add_f32_e32 v80, 0, v138
	v_add_f32_e32 v81, 0, v139
	v_cvt_pk_bf16_f32 v76, v138, v140
	v_add_f32_e32 v80, v140, v80
	v_add_f32_e32 v81, v141, v81
	v_cvt_pk_bf16_f32 v77, v154, v156
	v_add_f32_e32 v80, v154, v80
	v_add_f32_e32 v81, v155, v81
	v_cvt_pk_bf16_f32 v78, v158, v162
	v_add_f32_e32 v80, v156, v80
	v_add_f32_e32 v81, v157, v81
	v_cvt_pk_bf16_f32 v79, v160, v186
	v_add_f32_e32 v80, v158, v80
	v_add_f32_e32 v81, v159, v81
	v_cvt_pk_bf16_f32 v84, v139, v141
	v_add_f32_e32 v80, v162, v80
	v_add_f32_e32 v81, v163, v81
	v_cvt_pk_bf16_f32 v85, v155, v157
	v_add_f32_e32 v80, v160, v80
	v_add_f32_e32 v81, v161, v81
	v_cvt_pk_bf16_f32 v86, v159, v163
	v_add_f32_e32 v80, v186, v80
	v_add_f32_e32 v81, v187, v81
	v_cvt_pk_bf16_f32 v87, v161, v187
	v_add_f32_e32 v80, v178, v80
	v_add_f32_e32 v81, v179, v81
	s_waitcnt lgkmcnt(0)
	v_mfma_f32_16x16x32_bf16 v[44:47], v[88:91], v[76:79], v[44:47]
	v_add_f32_e64 v80, v188, v80
	v_add_f32_e64 v81, v189, v81
	v_exp_f32_e32 v194, v72
	v_add_f32_e32 v80, v180, v80
	v_add_f32_e32 v81, v181, v81
	v_mfma_f32_16x16x32_bf16 v[4:7], v[88:91], v[84:87], v[4:7]
	ds_read2_b64 v[88:91], v92 offset0:136 offset1:140
	v_add_f32_e32 v80, v190, v80
	v_add_f32_e32 v81, v191, v81
	v_cvt_pk_bf16_f32 v72, v178, v188
	v_add_f32_e32 v80, v182, v80
	v_add_f32_e32 v81, v183, v81
	v_cvt_pk_bf16_f32 v73, v180, v190
	v_add_f32_e32 v80, v192, v80
	v_add_f32_e32 v81, v193, v81
	v_cvt_pk_bf16_f32 v74, v182, v192
	v_add_f32_e32 v80, v184, v80
	v_add_f32_e32 v81, v185, v81
	v_cvt_pk_bf16_f32 v75, v184, v194
	v_add_f32_e32 v80, v194, v80
	v_add_f32_e32 v81, v195, v81
	v_cvt_pk_bf16_f32 v82, v183, v193
	v_fma_f32 v130, v130, v136, v80
	v_fma_f32 v131, v131, v137, v81
	v_cvt_pk_bf16_f32 v80, v179, v189
	v_cvt_pk_bf16_f32 v81, v181, v191
	v_cvt_pk_bf16_f32 v83, v185, v195
	v_add_u32_e32 v92, 0x3800, v24
	s_waitcnt lgkmcnt(0)
	v_mfma_f32_16x16x32_bf16 v[44:47], v[88:91], v[72:75], v[44:47]
	v_mfma_f32_16x16x32_bf16 v[4:7], v[88:91], v[80:83], v[4:7]
	ds_read2_b64 v[88:91], v92 offset0:160 offset1:164
	s_waitcnt lgkmcnt(0)
	v_mfma_f32_16x16x32_bf16 v[52:55], v[88:91], v[76:79], v[52:55]
	v_mfma_f32_16x16x32_bf16 v[0:3], v[88:91], v[84:87], v[0:3]
	ds_read2_b64 v[88:91], v92 offset0:168 offset1:172
	v_add_u32_e32 v92, 0x4000, v24
	v_add_u32_e32 v24, 0x4800, v24
	s_waitcnt lgkmcnt(0)
	v_mfma_f32_16x16x32_bf16 v[52:55], v[88:91], v[72:75], v[52:55]
	v_mfma_f32_16x16x32_bf16 v[0:3], v[88:91], v[80:83], v[0:3]
	ds_read2_b64 v[88:91], v92 offset0:192 offset1:196
	s_waitcnt lgkmcnt(0)
	v_mfma_f32_16x16x32_bf16 v[56:59], v[88:91], v[76:79], v[56:59]
	v_mfma_f32_16x16x32_bf16 v[8:11], v[88:91], v[84:87], v[8:11]
	ds_read2_b64 v[88:91], v92 offset0:200 offset1:204
	s_waitcnt lgkmcnt(0)
	v_mfma_f32_16x16x32_bf16 v[56:59], v[88:91], v[72:75], v[56:59]
	v_mfma_f32_16x16x32_bf16 v[8:11], v[88:91], v[80:83], v[8:11]
	ds_read2_b64 v[88:91], v24 offset0:224 offset1:228
	s_waitcnt lgkmcnt(0)
	v_mfma_f32_16x16x32_bf16 v[68:71], v[88:91], v[76:79], v[68:71]
	ds_read2_b64 v[76:79], v24 offset0:232 offset1:236
	v_mov_b32_e32 v24, v125
	v_mfma_f32_16x16x32_bf16 v[12:15], v[88:91], v[84:87], v[12:15]
	s_waitcnt lgkmcnt(0)
	v_mfma_f32_16x16x32_bf16 v[68:71], v[76:79], v[72:75], v[68:71]
	v_mov_b32_e32 v72, v123
	v_mfma_f32_16x16x32_bf16 v[12:15], v[76:79], v[80:83], v[12:15]
